# softmax epilogue row-max pass: lane-local maxima of all 8 row groups first, cross-lane exchanges issued together
# baseline (speedup 1.0000x reference)
.LBB11_2048:
	v_mov_b32_e32 v142, v138
	v_mov_b32_e32 v136, v140
	v_readlane_b32 s50, v242, 52
	v_readlane_b32 s51, v242, 53
	v_max3_f32 v213, v126, s72, v127
	v_max3_f32 v213, v213, v128, v129
	v_max3_f32 v213, v213, v122, v123
	v_max3_f32 v213, v213, v124, v125
	v_max3_f32 v213, v213, v118, v119
	v_max3_f32 v213, v213, v120, v121
	v_max3_f32 v213, v213, v114, v115
	v_max3_f32 v213, v213, v116, v117
	v_max3_f32 v214, v110, s72, v111
	v_max3_f32 v214, v214, v112, v113
	v_max3_f32 v214, v214, v106, v107
	v_max3_f32 v214, v214, v108, v109
	v_max3_f32 v214, v214, v102, v103
	v_max3_f32 v214, v214, v104, v105
	v_max3_f32 v214, v214, v98, v99
	v_max3_f32 v214, v214, v100, v101
	v_max3_f32 v215, v94, s72, v95
	v_max3_f32 v215, v215, v96, v97
	v_max3_f32 v215, v215, v90, v91
	v_max3_f32 v215, v215, v92, v93
	v_max3_f32 v215, v215, v86, v87
	v_max3_f32 v215, v215, v88, v89
	v_max3_f32 v215, v215, v82, v83
	v_max3_f32 v215, v215, v84, v85
	v_max3_f32 v216, v78, s72, v79
	v_max3_f32 v216, v216, v80, v81
	v_max3_f32 v216, v216, v74, v75
	v_max3_f32 v216, v216, v76, v77
	v_max3_f32 v216, v216, v70, v71
	v_max3_f32 v216, v216, v72, v73
	v_max3_f32 v216, v216, v66, v67
	v_max3_f32 v216, v216, v68, v69
	v_max3_f32 v217, v62, s72, v63
	v_max3_f32 v217, v217, v64, v65
	v_max3_f32 v217, v217, v58, v59
	v_max3_f32 v217, v217, v60, v61
	v_max3_f32 v217, v217, v54, v55
	v_max3_f32 v217, v217, v56, v57
	v_max3_f32 v217, v217, v50, v51
	v_max3_f32 v217, v217, v52, v53
	v_max3_f32 v218, v46, s72, v47
	v_max3_f32 v218, v218, v48, v49
	v_max3_f32 v218, v218, v42, v43
	v_max3_f32 v218, v218, v44, v45
	v_max3_f32 v218, v218, v38, v39
	v_max3_f32 v218, v218, v40, v41
	v_max3_f32 v218, v218, v34, v35
	v_max3_f32 v218, v218, v36, v37
	v_max3_f32 v219, v30, s72, v31
	v_max3_f32 v219, v219, v32, v33
	v_max3_f32 v219, v219, v26, v27
	v_max3_f32 v219, v219, v28, v29
	v_max3_f32 v219, v219, v22, v23
	v_max3_f32 v219, v219, v24, v25
	v_max3_f32 v219, v219, v18, v19
	v_max3_f32 v219, v219, v20, v21
	v_max3_f32 v220, v14, s72, v15
	v_max3_f32 v220, v220, v16, v17
	v_max3_f32 v220, v220, v10, v11
	v_max3_f32 v220, v220, v12, v13
	v_max3_f32 v220, v220, v6, v7
	v_max3_f32 v220, v220, v8, v9
	v_max3_f32 v220, v220, v2, v3
	v_max3_f32 v220, v220, v4, v5
	ds_bpermute_b32 v221, v204, v213
	ds_bpermute_b32 v222, v204, v214
	ds_bpermute_b32 v223, v204, v215
	ds_bpermute_b32 v224, v204, v216
	ds_bpermute_b32 v225, v204, v217
	ds_bpermute_b32 v226, v204, v218
	ds_bpermute_b32 v227, v204, v219
	ds_bpermute_b32 v228, v204, v220
	v_lshl_add_u32 v137, v142, 4, s89
	s_waitcnt lgkmcnt(7)
	v_max_f32_e32 v221, v221, v221
	v_max_f32_e32 v213, v213, v221
	s_waitcnt lgkmcnt(6)
	v_max_f32_e32 v222, v222, v222
	v_max_f32_e32 v214, v214, v222
	s_waitcnt lgkmcnt(5)
	v_max_f32_e32 v223, v223, v223
	v_max_f32_e32 v215, v215, v223
	s_waitcnt lgkmcnt(4)
	v_max_f32_e32 v224, v224, v224
	v_max_f32_e32 v216, v216, v224
	s_waitcnt lgkmcnt(3)
	v_max_f32_e32 v225, v225, v225
	v_max_f32_e32 v217, v217, v225
	s_waitcnt lgkmcnt(2)
	v_max_f32_e32 v226, v226, v226
	v_max_f32_e32 v218, v218, v226
	s_waitcnt lgkmcnt(1)
	v_max_f32_e32 v227, v227, v227
	v_max_f32_e32 v219, v219, v227
	s_waitcnt lgkmcnt(0)
	v_max_f32_e32 v228, v228, v228
	v_max_f32_e32 v220, v220, v228
	ds_bpermute_b32 v221, v205, v213
	ds_bpermute_b32 v222, v205, v214
	ds_bpermute_b32 v223, v205, v215
	ds_bpermute_b32 v224, v205, v216
	ds_bpermute_b32 v225, v205, v217
	ds_bpermute_b32 v226, v205, v218
	ds_bpermute_b32 v227, v205, v219
	ds_bpermute_b32 v228, v205, v220
	s_and_saveexec_b64 s[10:11], s[12:13]
	s_waitcnt lgkmcnt(7)
	v_max_f32_e32 v221, v221, v221
	v_max_f32_e32 v213, v213, v213
	v_max_f32_e32 v213, v213, v221
	s_waitcnt lgkmcnt(6)
	v_max_f32_e32 v222, v222, v222
	v_max_f32_e32 v214, v214, v214
	v_max_f32_e32 v214, v214, v222
	s_waitcnt lgkmcnt(5)
	v_max_f32_e32 v223, v223, v223
	v_max_f32_e32 v215, v215, v215
	v_max_f32_e32 v215, v215, v223
	s_waitcnt lgkmcnt(4)
	v_max_f32_e32 v224, v224, v224
	v_max_f32_e32 v216, v216, v216
	v_max_f32_e32 v216, v216, v224
	s_waitcnt lgkmcnt(3)
	v_max_f32_e32 v225, v225, v225
	v_max_f32_e32 v217, v217, v217
	v_max_f32_e32 v217, v217, v225
	s_waitcnt lgkmcnt(2)
	v_max_f32_e32 v226, v226, v226
	v_max_f32_e32 v218, v218, v218
	v_max_f32_e32 v218, v218, v226
	s_waitcnt lgkmcnt(1)
	v_max_f32_e32 v227, v227, v227
	v_max_f32_e32 v219, v219, v219
	v_max_f32_e32 v219, v219, v227
	s_waitcnt lgkmcnt(0)
	v_max_f32_e32 v228, v228, v228
	v_max_f32_e32 v220, v220, v220
	v_max_f32_e32 v220, v220, v228
	ds_write_b32 v137, v213
	ds_write_b32 v137, v214 offset:256
	ds_write_b32 v137, v215 offset:512
	ds_write_b32 v137, v216 offset:768
	ds_write_b32 v137, v217 offset:2048
	ds_write_b32 v137, v218 offset:2304
	ds_write_b32 v137, v219 offset:2560
	ds_write_b32 v137, v220 offset:2816
